# nt cache policy on the once-read x loads (p0_rows) and the final f32 output stores (final_rows), on top of v4
# speedup vs baseline: 1.0075x; 1.0075x over previous
; DI void p0_rows(const float* x, bf16_t* out, sq_t* sq, int nrows, int gw, int NGW, int lane) {
;     for (int row0 = gw; row0 < nrows; row0 += 4 * NGW) {
;         f32x4 v[4][4];
; #pragma unroll
;         for (int u = 0; u < 4; ++u) { const int row = row0 + u * NGW; if (row < nrows) { const f32x4* xr = (const f32x4*)(x + (size_t)row * 1024) + lane;
; #pragma unroll
;                 for (int j = 0; j < 4; ++j) v[u][j] = xr[64 * j]; } }
.LBB0_315:
	s_ashr_i32 s13, s12, 31
	s_lshl_b64 s[0:1], s[12:13], 12
	v_lshl_add_u64 v[78:79], v[68:69], 0, s[0:1]
	s_waitcnt lgkmcnt(0)
	global_load_dwordx4 v[62:65], v[78:79], off nt
	global_load_dwordx4 v[58:61], v[78:79], off offset:1024 nt
	global_load_dwordx4 v[54:57], v[78:79], off offset:2048 nt
	global_load_dwordx4 v[50:53], v[78:79], off offset:3072 nt
	s_add_i32 s0, s12, s94
	s_cmpk_lt_i32 s0, 0x4000
	s_cselect_b64 s[16:17], -1, 0
	s_cmpk_gt_i32 s0, 0x3fff
	s_cbranch_scc1 .LBB0_317
	s_ashr_i32 s1, s0, 31
	s_lshl_b64 s[6:7], s[0:1], 12
	v_lshl_add_u64 v[78:79], v[68:69], 0, s[6:7]
	global_load_dwordx4 v[46:49], v[78:79], off nt
	global_load_dwordx4 v[42:45], v[78:79], off offset:1024 nt
	global_load_dwordx4 v[38:41], v[78:79], off offset:2048 nt
	global_load_dwordx4 v[34:37], v[78:79], off offset:3072 nt
.LBB0_317:
	s_add_i32 s8, s20, s12
	s_cmpk_lt_i32 s8, 0x4000
	s_cselect_b64 s[14:15], -1, 0
	s_cmpk_gt_i32 s8, 0x3fff
	s_cbranch_scc1 .LBB0_319
	s_ashr_i32 s9, s8, 31
	s_lshl_b64 s[6:7], s[8:9], 12
	v_lshl_add_u64 v[78:79], v[68:69], 0, s[6:7]
	global_load_dwordx4 v[30:33], v[78:79], off nt
	global_load_dwordx4 v[26:29], v[78:79], off offset:1024 nt
	global_load_dwordx4 v[22:25], v[78:79], off offset:2048 nt
	global_load_dwordx4 v[18:21], v[78:79], off offset:3072 nt
.LBB0_319:
	s_add_i32 s6, s81, s12
	s_cmpk_lt_i32 s6, 0x4000
	s_cselect_b64 s[10:11], -1, 0
	s_cmpk_gt_i32 s6, 0x3fff
	s_cbranch_scc1 .LBB0_321
	s_ashr_i32 s7, s6, 31
	s_lshl_b64 s[18:19], s[6:7], 12
	v_lshl_add_u64 v[78:79], v[68:69], 0, s[18:19]
	global_load_dwordx4 v[14:17], v[78:79], off nt
	global_load_dwordx4 v[10:13], v[78:79], off offset:1024 nt
	global_load_dwordx4 v[6:9], v[78:79], off offset:2048 nt
	global_load_dwordx4 v[2:5], v[78:79], off offset:3072 nt

; DI void final_rows(const bf16_t* x, const sq_t* sq, const float* g, float* out, int nrows, int gw, int NGW, int lane) {
;     ...
;         for (int u = 0; u < 4; ++u) { const int row = row0 + u * NGW; if (row < nrows) { f32x4* o = (f32x4*)(out + (size_t)row * 1024) + lane;
; #pragma unroll
;                 for (int j = 0; j < 4; ++j) { const f32x4 gg = ((const f32x4*)g)[lane + 64 * j]; const float r = rstd[u];
;                     f32x4 y; y[0] = bflo(v[u][j].x) * r * gg[0]; y[1] = bfhi(v[u][j].x) * r * gg[1]; y[2] = bflo(v[u][j].y) * r * gg[2]; y[3] = bfhi(v[u][j].y) * r * gg[3]; o[64 * j] = y; } } }
.LBB0_375:
	global_load_dwordx4 v[44:47], v[10:11], off
	s_waitcnt vmcnt(4)
	v_lshlrev_b32_e32 v48, 16, v42
	v_and_b32_e32 v49, 0xffff0000, v42
	v_lshlrev_b32_e32 v42, 16, v43
	v_and_b32_e32 v43, 0xffff0000, v43
	s_lshl_b64 s[6:7], s[18:19], 12
	v_pk_mul_f32 v[48:49], v[0:1], v[48:49] op_sel_hi:[0,1]
	v_pk_mul_f32 v[52:53], v[0:1], v[42:43] op_sel_hi:[0,1]
	v_lshl_add_u64 v[50:51], v[8:9], 0, s[6:7]
	s_andn2_b64 vcc, exec, s[24:25]
	s_waitcnt vmcnt(0)
	v_pk_mul_f32 v[42:43], v[44:45], v[48:49]
	v_pk_mul_f32 v[44:45], v[46:47], v[52:53]
	global_store_dwordx4 v[50:51], v[42:45], off nt
	global_load_dwordx4 v[42:45], v[10:11], off offset:1024
	v_lshlrev_b32_e32 v46, 16, v40
	v_and_b32_e32 v47, 0xffff0000, v40
	v_lshlrev_b32_e32 v40, 16, v41
	v_and_b32_e32 v41, 0xffff0000, v41
	v_pk_mul_f32 v[46:47], v[0:1], v[46:47] op_sel_hi:[0,1]
	v_pk_mul_f32 v[48:49], v[0:1], v[40:41] op_sel_hi:[0,1]
	s_waitcnt vmcnt(0)
	v_pk_mul_f32 v[40:41], v[46:47], v[42:43]
	v_pk_mul_f32 v[42:43], v[48:49], v[44:45]
	global_store_dwordx4 v[50:51], v[40:43], off offset:1024 nt
	global_load_dwordx4 v[40:43], v[10:11], off offset:2048
	v_lshlrev_b32_e32 v44, 16, v38
	v_and_b32_e32 v45, 0xffff0000, v38
	v_lshlrev_b32_e32 v38, 16, v39
	v_and_b32_e32 v39, 0xffff0000, v39
	v_pk_mul_f32 v[44:45], v[0:1], v[44:45] op_sel_hi:[0,1]
	v_pk_mul_f32 v[46:47], v[0:1], v[38:39] op_sel_hi:[0,1]
	s_waitcnt vmcnt(0)
	v_pk_mul_f32 v[38:39], v[44:45], v[40:41]
	v_pk_mul_f32 v[40:41], v[46:47], v[42:43]
	global_store_dwordx4 v[50:51], v[38:41], off offset:2048 nt
	global_load_dwordx4 v[38:41], v[10:11], off offset:3072
	v_lshlrev_b32_e32 v42, 16, v36
	v_and_b32_e32 v43, 0xffff0000, v36
	v_lshlrev_b32_e32 v36, 16, v37
	v_and_b32_e32 v37, 0xffff0000, v37
	v_pk_mul_f32 v[42:43], v[0:1], v[42:43] op_sel_hi:[0,1]
	v_pk_mul_f32 v[44:45], v[0:1], v[36:37] op_sel_hi:[0,1]
	s_waitcnt vmcnt(0)
	v_pk_mul_f32 v[36:37], v[42:43], v[38:39]
	v_pk_mul_f32 v[38:39], v[44:45], v[40:41]
	global_store_dwordx4 v[50:51], v[36:39], off offset:3072 nt
	s_cbranch_vccnz .LBB0_378
	global_load_dwordx4 v[36:39], v[10:11], off
	s_ashr_i32 s17, s16, 31
	v_lshlrev_b32_e32 v40, 16, v34
	v_and_b32_e32 v41, 0xffff0000, v34
	v_lshlrev_b32_e32 v42, 16, v35
	v_and_b32_e32 v43, 0xffff0000, v35
	s_lshl_b64 s[6:7], s[16:17], 12
	v_pk_mul_f32 v[40:41], v[0:1], v[40:41] op_sel:[1,0]
	v_pk_mul_f32 v[42:43], v[0:1], v[42:43] op_sel:[1,0]
	v_lshl_add_u64 v[44:45], v[8:9], 0, s[6:7]
	s_waitcnt vmcnt(0)
	v_pk_mul_f32 v[36:37], v[40:41], v[36:37]
	v_pk_mul_f32 v[38:39], v[42:43], v[38:39]
	global_store_dwordx4 v[44:45], v[36:39], off nt
	global_load_dwordx4 v[36:39], v[10:11], off offset:1024
	v_lshlrev_b32_e32 v40, 16, v32
	v_and_b32_e32 v41, 0xffff0000, v32
	v_lshlrev_b32_e32 v42, 16, v33
	v_and_b32_e32 v43, 0xffff0000, v33
	v_pk_mul_f32 v[40:41], v[0:1], v[40:41] op_sel:[1,0]
	v_pk_mul_f32 v[42:43], v[0:1], v[42:43] op_sel:[1,0]
	s_waitcnt vmcnt(0)
	v_pk_mul_f32 v[36:37], v[40:41], v[36:37]
	v_pk_mul_f32 v[38:39], v[42:43], v[38:39]
	global_store_dwordx4 v[44:45], v[36:39], off offset:1024 nt
	global_load_dwordx4 v[36:39], v[10:11], off offset:2048
	v_lshlrev_b32_e32 v40, 16, v30
	v_and_b32_e32 v41, 0xffff0000, v30
	v_lshlrev_b32_e32 v42, 16, v31
	v_and_b32_e32 v43, 0xffff0000, v31
	v_pk_mul_f32 v[40:41], v[0:1], v[40:41] op_sel:[1,0]
	v_pk_mul_f32 v[42:43], v[0:1], v[42:43] op_sel:[1,0]
	s_waitcnt vmcnt(0)
	v_pk_mul_f32 v[36:37], v[40:41], v[36:37]
	v_pk_mul_f32 v[38:39], v[42:43], v[38:39]
	global_store_dwordx4 v[44:45], v[36:39], off offset:2048 nt
	global_load_dwordx4 v[36:39], v[10:11], off offset:3072
	v_lshlrev_b32_e32 v40, 16, v28
	v_and_b32_e32 v41, 0xffff0000, v28
	v_lshlrev_b32_e32 v42, 16, v29
	v_and_b32_e32 v43, 0xffff0000, v29
	v_pk_mul_f32 v[40:41], v[0:1], v[40:41] op_sel:[1,0]
	v_pk_mul_f32 v[42:43], v[0:1], v[42:43] op_sel:[1,0]
	s_waitcnt vmcnt(0)
	v_pk_mul_f32 v[36:37], v[40:41], v[36:37]
	v_pk_mul_f32 v[38:39], v[42:43], v[38:39]
	global_store_dwordx4 v[44:45], v[36:39], off offset:3072 nt
	s_andn2_b64 vcc, exec, s[28:29]
	s_cbranch_vccz .LBB0_379

; DI void final_rows(const bf16_t* x, const sq_t* sq, const float* g, float* out, int nrows, int gw, int NGW, int lane) {
;     ...
;         for (int u = 0; u < 4; ++u) { const int row = row0 + u * NGW; if (row < nrows) { f32x4* o = (f32x4*)(out + (size_t)row * 1024) + lane;
; #pragma unroll
;                 for (int j = 0; j < 4; ++j) { const f32x4 gg = ((const f32x4*)g)[lane + 64 * j]; const float r = rstd[u];
;                     f32x4 y; y[0] = bflo(v[u][j].x) * r * gg[0]; y[1] = bfhi(v[u][j].x) * r * gg[1]; y[2] = bflo(v[u][j].y) * r * gg[2]; y[3] = bfhi(v[u][j].y) * r * gg[3]; o[64 * j] = y; } } }
.LBB0_379:
	global_load_dwordx4 v[36:39], v[10:11], off
	s_ashr_i32 s23, s22, 31
	v_lshlrev_b32_e32 v40, 16, v26
	v_and_b32_e32 v41, 0xffff0000, v26
	v_lshlrev_b32_e32 v42, 16, v27
	v_and_b32_e32 v43, 0xffff0000, v27
	s_lshl_b64 s[6:7], s[22:23], 12
	v_pk_mul_f32 v[40:41], v[2:3], v[40:41] op_sel_hi:[0,1]
	v_pk_mul_f32 v[42:43], v[2:3], v[42:43] op_sel_hi:[0,1]
	v_lshl_add_u64 v[44:45], v[8:9], 0, s[6:7]
	s_waitcnt vmcnt(0)
	v_pk_mul_f32 v[36:37], v[40:41], v[36:37]
	v_pk_mul_f32 v[38:39], v[42:43], v[38:39]
	global_store_dwordx4 v[44:45], v[36:39], off nt
	global_load_dwordx4 v[36:39], v[10:11], off offset:1024
	v_lshlrev_b32_e32 v40, 16, v24
	v_and_b32_e32 v41, 0xffff0000, v24
	v_lshlrev_b32_e32 v42, 16, v25
	v_and_b32_e32 v43, 0xffff0000, v25
	v_pk_mul_f32 v[40:41], v[2:3], v[40:41] op_sel_hi:[0,1]
	v_pk_mul_f32 v[42:43], v[2:3], v[42:43] op_sel_hi:[0,1]
	s_waitcnt vmcnt(0)
	v_pk_mul_f32 v[36:37], v[40:41], v[36:37]
	v_pk_mul_f32 v[38:39], v[42:43], v[38:39]
	global_store_dwordx4 v[44:45], v[36:39], off offset:1024 nt
	global_load_dwordx4 v[36:39], v[10:11], off offset:2048
	v_lshlrev_b32_e32 v40, 16, v22
	v_and_b32_e32 v41, 0xffff0000, v22
	v_lshlrev_b32_e32 v42, 16, v23
	v_and_b32_e32 v43, 0xffff0000, v23
	v_pk_mul_f32 v[40:41], v[2:3], v[40:41] op_sel_hi:[0,1]
	v_pk_mul_f32 v[42:43], v[2:3], v[42:43] op_sel_hi:[0,1]
	s_waitcnt vmcnt(0)
	v_pk_mul_f32 v[36:37], v[40:41], v[36:37]
	v_pk_mul_f32 v[38:39], v[42:43], v[38:39]
	global_store_dwordx4 v[44:45], v[36:39], off offset:2048 nt
	global_load_dwordx4 v[36:39], v[10:11], off offset:3072
	v_lshlrev_b32_e32 v40, 16, v20
	v_and_b32_e32 v41, 0xffff0000, v20
	v_lshlrev_b32_e32 v42, 16, v21
	v_and_b32_e32 v43, 0xffff0000, v21
	v_pk_mul_f32 v[40:41], v[2:3], v[40:41] op_sel_hi:[0,1]
	v_pk_mul_f32 v[42:43], v[2:3], v[42:43] op_sel_hi:[0,1]
	s_waitcnt vmcnt(0)
	v_pk_mul_f32 v[36:37], v[40:41], v[36:37]
	v_pk_mul_f32 v[38:39], v[42:43], v[38:39]
	global_store_dwordx4 v[44:45], v[36:39], off offset:3072 nt
	s_andn2_b64 vcc, exec, s[26:27]
	s_cbranch_vccnz .LBB0_368
.LBB0_380:
	global_load_dwordx4 v[36:39], v[10:11], off
	s_ashr_i32 s21, s20, 31
	v_lshlrev_b32_e32 v40, 16, v18
	v_and_b32_e32 v41, 0xffff0000, v18
	v_mov_b32_e32 v0, v3
	v_lshlrev_b32_e32 v42, 16, v19
	v_and_b32_e32 v43, 0xffff0000, v19
	s_lshl_b64 s[6:7], s[20:21], 12
	v_pk_mul_f32 v[40:41], v[0:1], v[40:41] op_sel_hi:[0,1]
	v_pk_mul_f32 v[42:43], v[0:1], v[42:43] op_sel_hi:[0,1]
	v_lshl_add_u64 v[44:45], v[8:9], 0, s[6:7]
	s_waitcnt vmcnt(0)
	v_pk_mul_f32 v[36:37], v[40:41], v[36:37]
	v_pk_mul_f32 v[38:39], v[42:43], v[38:39]
	global_store_dwordx4 v[44:45], v[36:39], off nt
	global_load_dwordx4 v[36:39], v[10:11], off offset:1024
	v_lshlrev_b32_e32 v40, 16, v16
	v_and_b32_e32 v41, 0xffff0000, v16
	v_lshlrev_b32_e32 v42, 16, v17
	v_and_b32_e32 v43, 0xffff0000, v17
	v_pk_mul_f32 v[40:41], v[0:1], v[40:41] op_sel_hi:[0,1]
	v_pk_mul_f32 v[42:43], v[0:1], v[42:43] op_sel_hi:[0,1]
	s_waitcnt vmcnt(0)
	v_pk_mul_f32 v[36:37], v[40:41], v[36:37]
	v_pk_mul_f32 v[38:39], v[42:43], v[38:39]
	global_store_dwordx4 v[44:45], v[36:39], off offset:1024 nt
	global_load_dwordx4 v[36:39], v[10:11], off offset:2048
	v_lshlrev_b32_e32 v40, 16, v14
	v_and_b32_e32 v41, 0xffff0000, v14
	v_lshlrev_b32_e32 v42, 16, v15
	v_and_b32_e32 v43, 0xffff0000, v15
	v_pk_mul_f32 v[40:41], v[0:1], v[40:41] op_sel_hi:[0,1]
	v_pk_mul_f32 v[42:43], v[0:1], v[42:43] op_sel_hi:[0,1]
	s_waitcnt vmcnt(0)
	v_pk_mul_f32 v[36:37], v[40:41], v[36:37]
	v_pk_mul_f32 v[38:39], v[42:43], v[38:39]
	global_store_dwordx4 v[44:45], v[36:39], off offset:2048 nt
	global_load_dwordx4 v[36:39], v[10:11], off offset:3072
	v_lshlrev_b32_e32 v40, 16, v12
	v_and_b32_e32 v41, 0xffff0000, v12
	v_lshlrev_b32_e32 v42, 16, v13
	v_and_b32_e32 v43, 0xffff0000, v13
	v_pk_mul_f32 v[40:41], v[0:1], v[40:41] op_sel_hi:[0,1]
	v_pk_mul_f32 v[42:43], v[0:1], v[42:43] op_sel_hi:[0,1]
	s_waitcnt vmcnt(0)
	v_pk_mul_f32 v[36:37], v[40:41], v[36:37]
	v_pk_mul_f32 v[38:39], v[42:43], v[38:39]
	global_store_dwordx4 v[44:45], v[36:39], off offset:3072 nt
	s_branch .LBB0_368

; DI void p0_rows(const float* x, bf16_t* out, sq_t* sq, int nrows, int gw, int NGW, int lane) {
;     for (int row0 = gw; row0 < nrows; row0 += 4 * NGW) {
;         f32x4 v[4][4];
; #pragma unroll
;         for (int u = 0; u < 4; ++u) { const int row = row0 + u * NGW; if (row < nrows) { const f32x4* xr = (const f32x4*)(x + (size_t)row * 1024) + lane;
; #pragma unroll
;                 for (int j = 0; j < 4; ++j) v[u][j] = xr[64 * j]; } }
.LBB0_385:
	s_ashr_i32 s13, s12, 31
	s_lshl_b64 s[14:15], s[12:13], 12
	s_waitcnt lgkmcnt(0)
	v_lshl_add_u64 v[48:49], v[66:67], 0, s[14:15]
	global_load_dwordx4 v[60:63], v[48:49], off nt
	global_load_dwordx4 v[56:59], v[48:49], off offset:1024 nt
	global_load_dwordx4 v[52:55], v[48:49], off offset:2048 nt
	s_nop 0
	global_load_dwordx4 v[48:51], v[48:49], off offset:3072 nt
	s_add_i32 s14, s12, s94
	s_cmpk_lt_i32 s14, 0x4000
	s_cselect_b64 s[24:25], -1, 0
	s_cmpk_gt_i32 s14, 0x3fff
	s_cbranch_scc1 .LBB0_387
	s_ashr_i32 s15, s14, 31
	s_lshl_b64 s[16:17], s[14:15], 12
	v_lshl_add_u64 v[32:33], v[66:67], 0, s[16:17]
	global_load_dwordx4 v[44:47], v[32:33], off nt
	global_load_dwordx4 v[40:43], v[32:33], off offset:1024 nt
	global_load_dwordx4 v[36:39], v[32:33], off offset:2048 nt
	s_nop 0
	global_load_dwordx4 v[32:35], v[32:33], off offset:3072 nt
.LBB0_387:
	s_add_i32 s18, s31, s12
	s_cmpk_lt_i32 s18, 0x4000
	s_cselect_b64 s[22:23], -1, 0
	s_cmpk_gt_i32 s18, 0x3fff
	s_cbranch_scc1 .LBB0_389
	s_ashr_i32 s19, s18, 31
	s_lshl_b64 s[16:17], s[18:19], 12
	v_lshl_add_u64 v[16:17], v[66:67], 0, s[16:17]
	global_load_dwordx4 v[28:31], v[16:17], off nt
	global_load_dwordx4 v[24:27], v[16:17], off offset:1024 nt
	global_load_dwordx4 v[20:23], v[16:17], off offset:2048 nt
	s_nop 0
	global_load_dwordx4 v[16:19], v[16:17], off offset:3072 nt
.LBB0_389:
	s_add_i32 s16, s81, s12
	s_cmpk_lt_i32 s16, 0x4000
	s_cselect_b64 s[20:21], -1, 0
	s_cmpk_gt_i32 s16, 0x3fff
	s_cbranch_scc1 .LBB0_391
	s_ashr_i32 s17, s16, 31
	s_lshl_b64 s[26:27], s[16:17], 12
	v_lshl_add_u64 v[0:1], v[66:67], 0, s[26:27]
	global_load_dwordx4 v[12:15], v[0:1], off nt
	global_load_dwordx4 v[8:11], v[0:1], off offset:1024 nt
	global_load_dwordx4 v[4:7], v[0:1], off offset:2048 nt
	s_nop 0
	global_load_dwordx4 v[0:3], v[0:1], off offset:3072 nt

; DI void final_rows(const bf16_t* x, const sq_t* sq, const float* g, float* out, int nrows, int gw, int NGW, int lane) {
;     ...
;         for (int u = 0; u < 4; ++u) { const int row = row0 + u * NGW; if (row < nrows) { f32x4* o = (f32x4*)(out + (size_t)row * 1024) + lane;
; #pragma unroll
;                 for (int j = 0; j < 4; ++j) { const f32x4 gg = ((const f32x4*)g)[lane + 64 * j]; const float r = rstd[u];
;                     f32x4 y; y[0] = bflo(v[u][j].x) * r * gg[0]; y[1] = bfhi(v[u][j].x) * r * gg[1]; y[2] = bflo(v[u][j].y) * r * gg[2]; y[3] = bfhi(v[u][j].y) * r * gg[3]; o[64 * j] = y; } } }
.LBB0_1546:
	global_load_dwordx4 v[46:49], v[8:9], off
	v_lshlrev_b32_e32 v50, 16, v40
	v_and_b32_e32 v51, 0xffff0000, v40
	v_lshlrev_b32_e32 v40, 16, v41
	v_and_b32_e32 v41, 0xffff0000, v41
	s_lshl_b64 s[0:1], s[12:13], 12
	v_pk_mul_f32 v[50:51], v[0:1], v[50:51] op_sel_hi:[0,1]
	v_pk_mul_f32 v[40:41], v[0:1], v[40:41] op_sel_hi:[0,1]
	v_lshl_add_u64 v[52:53], v[6:7], 0, s[0:1]
	s_andn2_b64 vcc, exec, s[18:19]
	s_waitcnt vmcnt(0)
	v_pk_mul_f32 v[46:47], v[46:47], v[50:51]
	v_pk_mul_f32 v[48:49], v[48:49], v[40:41]
	global_store_dwordx4 v[52:53], v[46:49], off nt
	global_load_dwordx4 v[46:49], v[8:9], off offset:1024
	v_lshlrev_b32_e32 v40, 16, v38
	v_and_b32_e32 v41, 0xffff0000, v38
	v_lshlrev_b32_e32 v38, 16, v39
	v_and_b32_e32 v39, 0xffff0000, v39
	v_pk_mul_f32 v[40:41], v[0:1], v[40:41] op_sel_hi:[0,1]
	v_pk_mul_f32 v[50:51], v[0:1], v[38:39] op_sel_hi:[0,1]
	s_waitcnt vmcnt(0)
	v_pk_mul_f32 v[38:39], v[40:41], v[46:47]
	v_pk_mul_f32 v[40:41], v[50:51], v[48:49]
	global_store_dwordx4 v[52:53], v[38:41], off offset:1024 nt
	global_load_dwordx4 v[38:41], v[8:9], off offset:2048
	v_lshlrev_b32_e32 v46, 16, v36
	v_and_b32_e32 v47, 0xffff0000, v36
	v_lshlrev_b32_e32 v36, 16, v37
	v_and_b32_e32 v37, 0xffff0000, v37
	v_pk_mul_f32 v[46:47], v[0:1], v[46:47] op_sel_hi:[0,1]
	v_pk_mul_f32 v[48:49], v[0:1], v[36:37] op_sel_hi:[0,1]
	s_waitcnt vmcnt(0)
	v_pk_mul_f32 v[36:37], v[46:47], v[38:39]
	v_pk_mul_f32 v[38:39], v[48:49], v[40:41]
	global_store_dwordx4 v[52:53], v[36:39], off offset:2048 nt
	global_load_dwordx4 v[36:39], v[8:9], off offset:3072
	v_lshlrev_b32_e32 v40, 16, v34
	v_and_b32_e32 v41, 0xffff0000, v34
	v_lshlrev_b32_e32 v34, 16, v35
	v_and_b32_e32 v35, 0xffff0000, v35
	v_pk_mul_f32 v[40:41], v[0:1], v[40:41] op_sel_hi:[0,1]
	v_pk_mul_f32 v[46:47], v[0:1], v[34:35] op_sel_hi:[0,1]
	s_waitcnt vmcnt(0)
	v_pk_mul_f32 v[34:35], v[40:41], v[36:37]
	v_pk_mul_f32 v[36:37], v[46:47], v[38:39]
	global_store_dwordx4 v[52:53], v[34:37], off offset:3072 nt
	s_cbranch_vccnz .LBB0_1549
	global_load_dwordx4 v[34:37], v[8:9], off
	s_ashr_i32 s7, s6, 31
	v_lshlrev_b32_e32 v38, 16, v32
	v_and_b32_e32 v39, 0xffff0000, v32
	v_lshlrev_b32_e32 v40, 16, v33
	v_and_b32_e32 v41, 0xffff0000, v33
	s_lshl_b64 s[0:1], s[6:7], 12
	v_pk_mul_f32 v[38:39], v[0:1], v[38:39] op_sel:[1,0]
	v_pk_mul_f32 v[40:41], v[0:1], v[40:41] op_sel:[1,0]
	v_lshl_add_u64 v[46:47], v[6:7], 0, s[0:1]
	s_waitcnt vmcnt(0)
	v_pk_mul_f32 v[34:35], v[38:39], v[34:35]
	v_pk_mul_f32 v[36:37], v[40:41], v[36:37]
	global_store_dwordx4 v[46:47], v[34:37], off nt
	global_load_dwordx4 v[34:37], v[8:9], off offset:1024
	v_lshlrev_b32_e32 v38, 16, v24
	v_and_b32_e32 v39, 0xffff0000, v24
	v_lshlrev_b32_e32 v40, 16, v25
	v_and_b32_e32 v41, 0xffff0000, v25
	v_pk_mul_f32 v[38:39], v[0:1], v[38:39] op_sel:[1,0]
	v_pk_mul_f32 v[40:41], v[0:1], v[40:41] op_sel:[1,0]
	s_waitcnt vmcnt(0)
	v_pk_mul_f32 v[34:35], v[38:39], v[34:35]
	v_pk_mul_f32 v[36:37], v[40:41], v[36:37]
	global_store_dwordx4 v[46:47], v[34:37], off offset:1024 nt
	global_load_dwordx4 v[34:37], v[8:9], off offset:2048
	v_lshlrev_b32_e32 v38, 16, v22
	v_and_b32_e32 v39, 0xffff0000, v22
	v_lshlrev_b32_e32 v40, 16, v23
	v_and_b32_e32 v41, 0xffff0000, v23
	v_pk_mul_f32 v[38:39], v[0:1], v[38:39] op_sel:[1,0]
	v_pk_mul_f32 v[40:41], v[0:1], v[40:41] op_sel:[1,0]
	s_waitcnt vmcnt(0)
	v_pk_mul_f32 v[34:35], v[38:39], v[34:35]
	v_pk_mul_f32 v[36:37], v[40:41], v[36:37]
	global_store_dwordx4 v[46:47], v[34:37], off offset:2048 nt
	global_load_dwordx4 v[34:37], v[8:9], off offset:3072
	v_lshlrev_b32_e32 v38, 16, v30
	v_and_b32_e32 v39, 0xffff0000, v30
	v_lshlrev_b32_e32 v40, 16, v31
	v_and_b32_e32 v41, 0xffff0000, v31
	v_pk_mul_f32 v[38:39], v[0:1], v[38:39] op_sel:[1,0]
	v_pk_mul_f32 v[40:41], v[0:1], v[40:41] op_sel:[1,0]
	s_waitcnt vmcnt(0)
	v_pk_mul_f32 v[34:35], v[38:39], v[34:35]
	v_pk_mul_f32 v[36:37], v[40:41], v[36:37]
	global_store_dwordx4 v[46:47], v[34:37], off offset:3072 nt
	s_andn2_b64 vcc, exec, s[16:17]
	s_cbranch_vccz .LBB0_1550

; DI void final_rows(const bf16_t* x, const sq_t* sq, const float* g, float* out, int nrows, int gw, int NGW, int lane) {
;     ...
;         for (int u = 0; u < 4; ++u) { const int row = row0 + u * NGW; if (row < nrows) { f32x4* o = (f32x4*)(out + (size_t)row * 1024) + lane;
; #pragma unroll
;                 for (int j = 0; j < 4; ++j) { const f32x4 gg = ((const f32x4*)g)[lane + 64 * j]; const float r = rstd[u];
;                     f32x4 y; y[0] = bflo(v[u][j].x) * r * gg[0]; y[1] = bfhi(v[u][j].x) * r * gg[1]; y[2] = bflo(v[u][j].y) * r * gg[2]; y[3] = bfhi(v[u][j].y) * r * gg[3]; o[64 * j] = y; } } }
.LBB0_1550:
	global_load_dwordx4 v[34:37], v[8:9], off
	s_ashr_i32 s11, s10, 31
	v_lshlrev_b32_e32 v38, 16, v28
	v_and_b32_e32 v39, 0xffff0000, v28
	v_lshlrev_b32_e32 v40, 16, v29
	v_and_b32_e32 v41, 0xffff0000, v29
	s_lshl_b64 s[0:1], s[10:11], 12
	v_pk_mul_f32 v[38:39], v[2:3], v[38:39] op_sel_hi:[0,1]
	v_pk_mul_f32 v[40:41], v[2:3], v[40:41] op_sel_hi:[0,1]
	v_lshl_add_u64 v[46:47], v[6:7], 0, s[0:1]
	s_waitcnt vmcnt(0)
	v_pk_mul_f32 v[34:35], v[38:39], v[34:35]
	v_pk_mul_f32 v[36:37], v[40:41], v[36:37]
	global_store_dwordx4 v[46:47], v[34:37], off nt
	global_load_dwordx4 v[34:37], v[8:9], off offset:1024
	v_lshlrev_b32_e32 v38, 16, v16
	v_and_b32_e32 v39, 0xffff0000, v16
	v_lshlrev_b32_e32 v40, 16, v17
	v_and_b32_e32 v41, 0xffff0000, v17
	v_pk_mul_f32 v[38:39], v[2:3], v[38:39] op_sel_hi:[0,1]
	v_pk_mul_f32 v[40:41], v[2:3], v[40:41] op_sel_hi:[0,1]
	s_waitcnt vmcnt(0)
	v_pk_mul_f32 v[34:35], v[38:39], v[34:35]
	v_pk_mul_f32 v[36:37], v[40:41], v[36:37]
	global_store_dwordx4 v[46:47], v[34:37], off offset:1024 nt
	global_load_dwordx4 v[34:37], v[8:9], off offset:2048
	v_lshlrev_b32_e32 v38, 16, v14
	v_and_b32_e32 v39, 0xffff0000, v14
	v_lshlrev_b32_e32 v40, 16, v15
	v_and_b32_e32 v41, 0xffff0000, v15
	v_pk_mul_f32 v[38:39], v[2:3], v[38:39] op_sel_hi:[0,1]
	v_pk_mul_f32 v[40:41], v[2:3], v[40:41] op_sel_hi:[0,1]
	s_waitcnt vmcnt(0)
	v_pk_mul_f32 v[34:35], v[38:39], v[34:35]
	v_pk_mul_f32 v[36:37], v[40:41], v[36:37]
	global_store_dwordx4 v[46:47], v[34:37], off offset:2048 nt
	global_load_dwordx4 v[34:37], v[8:9], off offset:3072
	v_lshlrev_b32_e32 v38, 16, v26
	v_and_b32_e32 v39, 0xffff0000, v26
	v_lshlrev_b32_e32 v40, 16, v27
	v_and_b32_e32 v41, 0xffff0000, v27
	v_pk_mul_f32 v[38:39], v[2:3], v[38:39] op_sel_hi:[0,1]
	v_pk_mul_f32 v[40:41], v[2:3], v[40:41] op_sel_hi:[0,1]
	s_waitcnt vmcnt(0)
	v_pk_mul_f32 v[34:35], v[38:39], v[34:35]
	v_pk_mul_f32 v[36:37], v[40:41], v[36:37]
	global_store_dwordx4 v[46:47], v[34:37], off offset:3072 nt
	s_andn2_b64 vcc, exec, s[14:15]
	s_cbranch_vccnz .LBB0_1539
.LBB0_1551:
	global_load_dwordx4 v[34:37], v[8:9], off
	s_ashr_i32 s9, s8, 31
	v_lshlrev_b32_e32 v38, 16, v20
	v_and_b32_e32 v39, 0xffff0000, v20
	v_mov_b32_e32 v0, v3
	v_lshlrev_b32_e32 v40, 16, v21
	v_and_b32_e32 v41, 0xffff0000, v21
	s_lshl_b64 s[0:1], s[8:9], 12
	v_pk_mul_f32 v[38:39], v[0:1], v[38:39] op_sel_hi:[0,1]
	v_pk_mul_f32 v[40:41], v[0:1], v[40:41] op_sel_hi:[0,1]
	v_lshl_add_u64 v[46:47], v[6:7], 0, s[0:1]
	s_waitcnt vmcnt(0)
	v_pk_mul_f32 v[34:35], v[38:39], v[34:35]
	v_pk_mul_f32 v[36:37], v[40:41], v[36:37]
	global_store_dwordx4 v[46:47], v[34:37], off nt
	global_load_dwordx4 v[34:37], v[8:9], off offset:1024
	v_lshlrev_b32_e32 v38, 16, v12
	v_and_b32_e32 v39, 0xffff0000, v12
	v_lshlrev_b32_e32 v40, 16, v13
	v_and_b32_e32 v41, 0xffff0000, v13
	v_pk_mul_f32 v[38:39], v[0:1], v[38:39] op_sel_hi:[0,1]
	v_pk_mul_f32 v[40:41], v[0:1], v[40:41] op_sel_hi:[0,1]
	s_waitcnt vmcnt(0)
	v_pk_mul_f32 v[34:35], v[38:39], v[34:35]
	v_pk_mul_f32 v[36:37], v[40:41], v[36:37]
	global_store_dwordx4 v[46:47], v[34:37], off offset:1024 nt
	global_load_dwordx4 v[34:37], v[8:9], off offset:2048
	v_lshlrev_b32_e32 v38, 16, v10
	v_and_b32_e32 v39, 0xffff0000, v10
	v_lshlrev_b32_e32 v40, 16, v11
	v_and_b32_e32 v41, 0xffff0000, v11
	v_pk_mul_f32 v[38:39], v[0:1], v[38:39] op_sel_hi:[0,1]
	v_pk_mul_f32 v[40:41], v[0:1], v[40:41] op_sel_hi:[0,1]
	s_waitcnt vmcnt(0)
	v_pk_mul_f32 v[34:35], v[38:39], v[34:35]
	v_pk_mul_f32 v[36:37], v[40:41], v[36:37]
	global_store_dwordx4 v[46:47], v[34:37], off offset:2048 nt
	global_load_dwordx4 v[34:37], v[8:9], off offset:3072
	v_lshlrev_b32_e32 v38, 16, v18
	v_and_b32_e32 v39, 0xffff0000, v18
	v_lshlrev_b32_e32 v40, 16, v19
	v_and_b32_e32 v41, 0xffff0000, v19
	v_pk_mul_f32 v[38:39], v[0:1], v[38:39] op_sel_hi:[0,1]
	v_pk_mul_f32 v[40:41], v[0:1], v[40:41] op_sel_hi:[0,1]
	s_waitcnt vmcnt(0)
	v_pk_mul_f32 v[34:35], v[38:39], v[34:35]
	v_pk_mul_f32 v[36:37], v[40:41], v[36:37]
	global_store_dwordx4 v[46:47], v[34:37], off offset:3072 nt
	s_branch .LBB0_1539
